# scan prefix spread over 64 workgroups (one 16-column chain per workgroup, one wave) instead of 16x4 waves; fp8 table conversion on the remaining 448
# speedup vs baseline: 1.1115x; 1.0383x over previous
; #define PHASE(n, body) if (p.phase_lo <= (n) && (n) < p.phase_hi) { if ((DBL_MASK >> (n)) & 1) { body; xcd_barrier(xb); } body; if ((n) + 1 < p.phase_hi) { if (p.phase_lo < 0) cg::this_grid().sync(); xcd_barrier(xb); } }
; DI void convert_tables_fp8(const Params& p, int bid, int nb) {
;   const int lane = threadIdx.x & 63, wave = threadIdx.x >> 6;
;   for (int r0 = (bid * 4 + wave) * 4; r0 < 32768; r0 += nb * 16) {
;     float f[4][16];
; #pragma unroll
;     for (int rr = 0; rr < 4; rr++) {
;       const int r = r0 + rr;
;       const float* src = ((r >= 16384) ? p.pv : p.pu) + (size_t)(r & 16383) * 1024 + lane * 16;
; #pragma unroll
;       for (int i = 0; i < 4; i++) { float4 v = *(const float4*)(src + 4 * i); f[rr][4 * i] = v.x; f[rr][4 * i + 1] = v.y; f[rr][4 * i + 2] = v.z; f[rr][4 * i + 3] = v.w; }
;     }
; __global__ void __launch_bounds__(256, 2) fwd_megakernel(Params p) {
;     ...
;   PHASE(3, for (int tk = bid; tk < 512; tk += nb) phase_scan_seg(p, tk, smem); phase_sbattn(p, bid * 4 + (threadIdx.x >> 6), nb * 4); if (bid < 16) phase_scan_prefix(p, bid, smem); else convert_tables_fp8(p, bid - 16, nb - 16))
.LBB0_830:
	s_or_b64 exec, exec, s[46:47]
	s_cmp_gt_i32 s2, 63
	s_mov_b64 s[0:1], -1
	s_cbranch_scc0 .LBB0_843
	s_lshl_b32 s0, s2, 4
	s_addk_i32 s0, 0xfc00
	v_and_b32_e32 v2, 60, v149
	s_waitcnt vmcnt(55)
	v_add_u32_e32 v60, s0, v2
	s_mov_b32 s0, 0x8000
	v_cmp_gt_i32_e32 vcc, s0, v60
	s_and_saveexec_b64 s[12:13], vcc
	s_cbranch_execz .LBB0_842
	v_mbcnt_lo_u32_b32 v4, -1, 0
	v_mbcnt_hi_u32_b32 v4, -1, v4
	v_and_b32_e32 v3, 63, v1
	v_and_b32_e32 v5, 64, v4
	v_lshlrev_b32_e32 v2, 4, v3
	v_add_u32_e32 v5, 64, v5
	v_cmp_eq_u32_e64 s[0:1], 0, v3
	v_xor_b32_e32 v3, 32, v4
	v_cmp_lt_i32_e32 vcc, v3, v5
	v_readlane_b32 s56, v253, 31
	v_readlane_b32 s57, v253, 32
	v_cndmask_b32_e32 v3, v4, v3, vcc
	s_waitcnt vmcnt(52)
	v_lshlrev_b32_e32 v62, 2, v3
	v_xor_b32_e32 v3, 16, v4
	v_cmp_lt_i32_e32 vcc, v3, v5
	v_readlane_b32 s58, v253, 33
	v_readlane_b32 s59, v253, 34
	v_cndmask_b32_e32 v3, v4, v3, vcc
	v_lshlrev_b32_e32 v63, 2, v3
	v_xor_b32_e32 v3, 8, v4
	v_cmp_lt_i32_e32 vcc, v3, v5
	v_readlane_b32 s60, v253, 35
	v_readlane_b32 s61, v253, 36
	v_cndmask_b32_e32 v3, v4, v3, vcc
	v_lshlrev_b32_e32 v64, 2, v3
	v_xor_b32_e32 v3, 4, v4
	v_cmp_lt_i32_e32 vcc, v3, v5
	v_readlane_b32 s62, v253, 37
	v_readlane_b32 s63, v253, 38
	v_cndmask_b32_e32 v3, v4, v3, vcc
	v_lshlrev_b32_e32 v65, 2, v3
	v_xor_b32_e32 v3, 2, v4
	v_cmp_lt_i32_e32 vcc, v3, v5
	v_readlane_b32 s64, v253, 39
	v_readlane_b32 s65, v253, 40
	v_cndmask_b32_e32 v3, v4, v3, vcc
	v_lshlrev_b32_e32 v66, 2, v3
	v_xor_b32_e32 v3, 1, v4
	v_cmp_lt_i32_e32 vcc, v3, v5
	v_readlane_b32 s66, v253, 41
	v_readlane_b32 s67, v253, 42
	v_readlane_b32 s68, v253, 43
	v_readlane_b32 s69, v253, 44
	v_readlane_b32 s70, v253, 45
	v_readlane_b32 s71, v253, 46
	v_lshlrev_b32_e32 v6, 11, v1
	v_readlane_b32 s4, v253, 8
	v_cndmask_b32_e32 v3, v4, v3, vcc
	v_mov_b32_e32 v69, s71
	s_waitcnt vmcnt(51)
	v_mov_b32_e32 v71, s70
	v_readlane_b32 s56, v252, 1
	v_mov_b32_e32 v55, 0
	v_and_b32_e32 v61, 0x1c000, v6
	v_lshlrev_b32_e32 v6, 4, v1
	s_lshl_b32 s18, s4, 4
	v_lshlrev_b32_e32 v67, 2, v3
	v_lshlrev_b32_e32 v3, 12, v99
	s_lshl_b32 s19, s4, 14
	v_readlane_b32 s66, v252, 11
	v_readlane_b32 s67, v252, 12
	v_readlane_b32 s68, v252, 13
	v_readlane_b32 s69, v252, 14
	v_and_b32_e32 v56, 0x70, v6
	v_mov_b32_e32 v57, v55
	s_addk_i32 s18, 0xfc00
	v_lshl_add_u32 v68, s2, 14, v3
	s_add_i32 s19, s19, 0xfff00000
	s_mov_b64 s[14:15], 0
	s_movk_i32 s20, 0x3fff
	v_mov_b32_e32 v70, s41
	v_mov_b32_e32 v72, s40
	v_lshlrev_b32_e32 v58, 2, v2
	v_mov_b32_e32 v59, v55
	s_movk_i32 s21, 0x3ffe
	s_mov_b32 s22, 0x43e00000
	v_mov_b32_e32 v73, s67
	s_waitcnt vmcnt(50)
	v_mov_b32_e32 v74, s69
	v_mov_b32_e32 v75, s66
	v_mov_b32_e32 v76, s68
	s_movk_i32 s23, 0x7fff
	v_readlane_b32 s5, v253, 9
	v_readlane_b32 s57, v252, 2
	v_readlane_b32 s58, v252, 3
	v_readlane_b32 s59, v252, 4
	v_readlane_b32 s60, v252, 5
	v_readlane_b32 s61, v252, 6
	v_readlane_b32 s62, v252, 7
	v_readlane_b32 s63, v252, 8
	v_readlane_b32 s64, v252, 9
	v_readlane_b32 s65, v252, 10
	v_readlane_b32 s70, v252, 15
	v_readlane_b32 s71, v252, 16
	s_branch .LBB0_834

; DI void convert_tables_fp8(const Params& p, int bid, int nb) {
;     ...
;   for (int r0 = (bid * 4 + wave) * 4; r0 < 32768; r0 += nb * 16) {
;     float f[4][16];
; #pragma unroll
;     for (int rr = 0; rr < 4; rr++) {
;       const int r = r0 + rr;
;       const float* src = ((r >= 16384) ? p.pv : p.pu) + (size_t)(r & 16383) * 1024 + lane * 16;
; #pragma unroll
;       for (int i = 0; i < 4; i++) { float4 v = *(const float4*)(src + 4 * i); f[rr][4 * i] = v.x; f[rr][4 * i + 1] = v.y; f[rr][4 * i + 2] = v.z; f[rr][4 * i + 3] = v.w; }
;     }
;     float m[4];
; #pragma unroll
;     for (int rr = 0; rr < 4; rr++) {
;       float mm = 0.f;
; #pragma unroll
;       for (int i = 0; i < 16; i++) mm = fmaxf(mm, fabsf(f[rr][i]));
;       m[rr] = mm;
;     }
; #pragma unroll
;     for (int o = 32; o >= 1; o >>= 1)
; #pragma unroll
;       for (int rr = 0; rr < 4; rr++) m[rr] = fmaxf(m[rr], __shfl_xor(m[rr], o));
.LBB0_834:
	v_add_u32_e32 v4, 0xfff00000, v68
	v_cmp_lt_i32_e64 s[10:11], s20, v60
	v_and_b32_e32 v4, 0xfff000, v4
	v_add_u32_e32 v6, 0xfff00400, v68
	v_cndmask_b32_e64 v3, v69, v70, s[10:11]
	v_cndmask_b32_e64 v2, v71, v72, s[10:11]
	v_lshlrev_b32_e32 v54, 2, v4
	v_cmp_lt_i32_e64 s[8:9], s21, v60
	v_and_b32_e32 v6, 0xfff400, v6
	v_lshl_add_u64 v[2:3], v[2:3], 0, v[54:55]
	v_cndmask_b32_e64 v5, v69, v70, s[8:9]
	v_cndmask_b32_e64 v4, v71, v72, s[8:9]
	v_lshlrev_b32_e32 v54, 2, v6
	v_add_u32_e32 v78, 2, v60
	v_add_u32_e32 v8, 0xfff00800, v68
	v_lshl_add_u64 v[2:3], v[2:3], 0, v[58:59]
	v_lshl_add_u64 v[4:5], v[4:5], 0, v[54:55]
	v_cmp_lt_i32_e64 s[6:7], s20, v78
	v_and_b32_e32 v8, 0xfff800, v8
	global_load_dwordx4 v[50:53], v[2:3], off offset:16
	global_load_dwordx4 v[86:89], v[2:3], off
	v_lshl_add_u64 v[4:5], v[4:5], 0, v[58:59]
	v_cndmask_b32_e64 v7, v69, v70, s[6:7]
	v_cndmask_b32_e64 v6, v71, v72, s[6:7]
	v_lshlrev_b32_e32 v54, 2, v8
	global_load_dwordx4 v[34:37], v[4:5], off offset:16
	global_load_dwordx4 v[38:41], v[4:5], off
	v_lshl_add_u64 v[6:7], v[6:7], 0, v[54:55]
	v_lshl_add_u64 v[18:19], v[6:7], 0, v[58:59]
	global_load_dwordx4 v[22:25], v[18:19], off
	v_add_u32_e32 v77, 3, v60
	v_add_u32_e32 v8, 0xfff00c00, v68
	v_cmp_lt_i32_e64 s[4:5], s20, v77
	v_and_b32_e32 v8, 0xfffc00, v8
	v_lshlrev_b32_e32 v54, 2, v8
	v_cndmask_b32_e64 v7, v69, v70, s[4:5]
	v_cndmask_b32_e64 v6, v71, v72, s[4:5]
	v_lshl_add_u64 v[6:7], v[6:7], 0, v[54:55]
	v_lshl_add_u64 v[80:81], v[6:7], 0, v[58:59]
	global_load_dwordx4 v[14:17], v[80:81], off
	global_load_dwordx4 v[90:93], v[2:3], off offset:32
	global_load_dwordx4 v[30:33], v[18:19], off offset:16
	global_load_dwordx4 v[46:49], v[4:5], off offset:32
	global_load_dwordx4 v[10:13], v[80:81], off offset:16
	global_load_dwordx4 v[94:97], v[2:3], off offset:48
	global_load_dwordx4 v[26:29], v[18:19], off offset:32
	global_load_dwordx4 v[42:45], v[4:5], off offset:48
	global_load_dwordx4 v[6:9], v[80:81], off offset:32
	s_nop 0
	global_load_dwordx4 v[18:21], v[18:19], off offset:48
	s_nop 0
	global_load_dwordx4 v[2:5], v[80:81], off offset:48
	s_waitcnt vmcnt(14)
	v_max3_f32 v54, |v86|, 0, |v87|
	v_max3_f32 v54, v54, |v88|, |v89|
	v_max3_f32 v54, v54, |v50|, |v51|
	v_max3_f32 v54, v54, |v52|, |v53|
	s_waitcnt vmcnt(12)
	v_max3_f32 v79, |v38|, 0, |v39|
	v_max3_f32 v79, v79, |v40|, |v41|
	v_max3_f32 v79, v79, |v34|, |v35|
	s_waitcnt vmcnt(11)
	v_max3_f32 v80, |v22|, 0, |v23|
	v_max3_f32 v80, v80, |v24|, |v25|
	s_waitcnt vmcnt(9)
	v_max3_f32 v54, v54, |v90|, |v91|
	v_max3_f32 v79, v79, |v36|, |v37|
	s_waitcnt vmcnt(8)
	v_max3_f32 v80, v80, |v30|, |v31|
	v_max3_f32 v54, v54, |v92|, |v93|
	s_waitcnt vmcnt(7)
	v_max3_f32 v79, v79, |v46|, |v47|
	v_max3_f32 v81, |v14|, 0, |v15|
	v_max3_f32 v80, v80, |v32|, |v33|
	s_waitcnt vmcnt(5)
	v_max3_f32 v54, v54, |v94|, |v95|
	v_max3_f32 v79, v79, |v48|, |v49|
	v_max3_f32 v81, v81, |v16|, |v17|
	s_waitcnt vmcnt(4)
	v_max3_f32 v80, v80, |v26|, |v27|
	v_max3_f32 v54, v54, |v96|, |v97|
	s_waitcnt vmcnt(3)
	v_max3_f32 v79, v79, |v42|, |v43|
	v_max3_f32 v81, v81, |v10|, |v11|
	v_max3_f32 v80, v80, |v28|, |v29|
	v_max3_f32 v79, v79, |v44|, |v45|
	ds_bpermute_b32 v82, v62, v54
	v_max3_f32 v81, v81, |v12|, |v13|
	s_waitcnt vmcnt(1)
	v_max3_f32 v80, v80, |v18|, |v19|
	ds_bpermute_b32 v83, v62, v79
	v_max3_f32 v81, v81, |v6|, |v7|
	v_max3_f32 v80, v80, |v20|, |v21|
	v_max3_f32 v81, v81, |v8|, |v9|
	ds_bpermute_b32 v84, v62, v80
	s_waitcnt vmcnt(0)
	v_max3_f32 v81, v81, |v2|, |v3|
	v_max3_f32 v81, v81, |v4|, |v5|
	s_waitcnt lgkmcnt(2)
	v_max_f32_e32 v82, v82, v82
	ds_bpermute_b32 v85, v62, v81
	v_max_f32_e32 v54, v54, v82
	s_waitcnt lgkmcnt(2)
	v_max_f32_e32 v82, v83, v83
	v_max_f32_e32 v79, v79, v82
	ds_bpermute_b32 v83, v63, v54
	s_waitcnt lgkmcnt(2)
	v_max_f32_e32 v82, v84, v84
	ds_bpermute_b32 v84, v63, v79
	v_max_f32_e32 v80, v80, v82
	s_waitcnt lgkmcnt(2)
	v_max_f32_e32 v82, v85, v85
	v_max_f32_e32 v81, v81, v82
	ds_bpermute_b32 v82, v63, v80
	s_waitcnt lgkmcnt(2)
	v_max_f32_e32 v83, v83, v83
	ds_bpermute_b32 v85, v63, v81
	v_max_f32_e32 v54, v54, v83
	s_waitcnt lgkmcnt(2)
	v_max_f32_e32 v83, v84, v84
	v_max_f32_e32 v79, v79, v83
	ds_bpermute_b32 v83, v64, v54
	ds_bpermute_b32 v84, v64, v79
	s_waitcnt lgkmcnt(3)
; DI void convert_tables_fp8(const Params& p, int bid, int nb) {
;     ...
;     float m[4];
; #pragma unroll
;     for (int rr = 0; rr < 4; rr++) {
;       float mm = 0.f;
; #pragma unroll
;       for (int i = 0; i < 16; i++) mm = fmaxf(mm, fabsf(f[rr][i]));
;       m[rr] = mm;
;     }
; #pragma unroll
;     for (int o = 32; o >= 1; o >>= 1)
; #pragma unroll
;       for (int rr = 0; rr < 4; rr++) m[rr] = fmaxf(m[rr], __shfl_xor(m[rr], o));
; #pragma unroll
;     for (int rr = 0; rr < 4; rr++) {
;       const int r = r0 + rr;
;       const bool isv = r >= 16384;
;       const int e = r & 16383;
;       const float inv = m[rr] > 0.f ? 448.f / m[rr] : 0.f;
;       u32x4 q;
; #pragma unroll
;       for (int i = 0; i < 4; i++) {
;         int w = __builtin_amdgcn_cvt_pk_fp8_f32(f[rr][4 * i] * inv, f[rr][4 * i + 1] * inv, 0, false);
;         w = __builtin_amdgcn_cvt_pk_fp8_f32(f[rr][4 * i + 2] * inv, f[rr][4 * i + 3] * inv, w, true);
;         q[i] = (unsigned)w;
;       }
;       unsigned char* dst = isv ? p.vb8 : p.ub8;
;       *(u32x4*)(dst + ((size_t)(lane >> 3) * 16384 + e) * 128 + (lane & 7) * 16) = q;
;       if (lane == 0) { if (isv) p.vscale[e] = m[rr] * (1.f / 448.f); else p.uscale[e] = m[rr] * (1.f / 448.f); }
;     }
	v_max_f32_e32 v82, v82, v82
	v_max_f32_e32 v80, v80, v82
	s_waitcnt lgkmcnt(2)
	v_max_f32_e32 v82, v85, v85
	v_max_f32_e32 v81, v81, v82
	ds_bpermute_b32 v82, v64, v80
	s_waitcnt lgkmcnt(2)
	v_max_f32_e32 v83, v83, v83
	ds_bpermute_b32 v85, v64, v81
	v_max_f32_e32 v54, v54, v83
	s_waitcnt lgkmcnt(2)
	v_max_f32_e32 v83, v84, v84
	v_max_f32_e32 v79, v79, v83
	ds_bpermute_b32 v83, v65, v54
	s_waitcnt lgkmcnt(2)
	v_max_f32_e32 v82, v82, v82
	ds_bpermute_b32 v84, v65, v79
	v_max_f32_e32 v80, v80, v82
	s_waitcnt lgkmcnt(2)
	v_max_f32_e32 v82, v85, v85
	v_max_f32_e32 v81, v81, v82
	s_waitcnt lgkmcnt(1)
	v_max_f32_e32 v82, v83, v83
	ds_bpermute_b32 v83, v65, v80
	v_max_f32_e32 v54, v54, v82
	s_waitcnt lgkmcnt(1)
	v_max_f32_e32 v82, v84, v84
	ds_bpermute_b32 v84, v65, v81
	v_max_f32_e32 v79, v79, v82
	s_waitcnt lgkmcnt(1)
	v_max_f32_e32 v82, v83, v83
	ds_bpermute_b32 v83, v66, v54
	v_max_f32_e32 v80, v80, v82
	s_waitcnt lgkmcnt(1)
	v_max_f32_e32 v82, v84, v84
	ds_bpermute_b32 v84, v66, v79
	v_max_f32_e32 v82, v81, v82
	s_waitcnt lgkmcnt(1)
	v_max_f32_e32 v81, v83, v83
	v_max_f32_e32 v54, v54, v81
	ds_bpermute_b32 v81, v66, v80
	ds_bpermute_b32 v85, v67, v54
	s_waitcnt lgkmcnt(2)
	v_max_f32_e32 v83, v84, v84
	ds_bpermute_b32 v84, v66, v82
	v_max_f32_e32 v83, v79, v83
	s_waitcnt lgkmcnt(2)
	v_max_f32_e32 v79, v81, v81
	v_max_f32_e32 v81, v80, v79
	s_waitcnt lgkmcnt(1)
	v_max_f32_e32 v80, v85, v85
	s_waitcnt lgkmcnt(0)
	v_max_f32_e32 v79, v84, v84
	v_max_f32_e32 v84, v54, v80
	v_div_scale_f32 v54, s[16:17], v84, v84, s22
	v_rcp_f32_e32 v98, v54
	v_max_f32_e32 v79, v82, v79
	ds_bpermute_b32 v85, v67, v83
	ds_bpermute_b32 v82, v67, v81
	v_fma_f32 v100, -v54, v98, 1.0
	v_fmac_f32_e32 v98, v100, v98
	v_div_scale_f32 v100, vcc, s22, v84, s22
	v_mul_f32_e32 v101, v100, v98
	v_fma_f32 v102, -v54, v101, v100
	v_fmac_f32_e32 v101, v102, v98
	v_fma_f32 v54, -v54, v101, v100
	v_div_fmas_f32 v54, v54, v98, v101
	v_div_fixup_f32 v54, v54, v84, s22
	v_cmp_lt_f32_e32 vcc, 0, v84
	ds_bpermute_b32 v80, v67, v79
	s_nop 0
	v_cndmask_b32_e32 v54, 0, v54, vcc
	v_mul_f32_e32 v98, v86, v54
	v_mul_f32_e32 v87, v87, v54
	v_mov_b32_e32 v86, v55
	v_cvt_pk_fp8_f32 v86, v98, v87
	v_mul_f32_e32 v50, v50, v54
	v_mul_f32_e32 v51, v51, v54
	v_mov_b32_e32 v87, v55
	v_cvt_pk_fp8_f32 v87, v50, v51
	v_mul_f32_e32 v88, v88, v54
	v_mul_f32_e32 v89, v89, v54
	v_mul_f32_e32 v50, v52, v54
	v_mul_f32_e32 v51, v53, v54
	v_cvt_pk_fp8_f32 v86, v88, v89 op_sel:[0,0,1]
	v_cvt_pk_fp8_f32 v87, v50, v51 op_sel:[0,0,1]
	v_mul_f32_e32 v50, v90, v54
	v_mul_f32_e32 v51, v91, v54
	v_mov_b32_e32 v88, v55
	v_cvt_pk_fp8_f32 v88, v50, v51
	v_mul_f32_e32 v52, v94, v54
	v_mul_f32_e32 v53, v95, v54
	v_mov_b32_e32 v89, v55
	v_cvt_pk_fp8_f32 v89, v52, v53
	v_mul_f32_e32 v50, v92, v54
	v_mul_f32_e32 v51, v93, v54
	v_cvt_pk_fp8_f32 v88, v50, v51 op_sel:[0,0,1]
	v_mul_f32_e32 v50, v96, v54
	v_mul_f32_e32 v51, v97, v54
	v_cvt_pk_fp8_f32 v89, v50, v51 op_sel:[0,0,1]
	v_and_b32_e32 v50, 0x3ffc, v60
	v_or_b32_e32 v51, v50, v61
	v_cndmask_b32_e64 v53, v73, v74, s[10:11]
	v_cndmask_b32_e64 v52, v75, v76, s[10:11]
	v_lshlrev_b32_e32 v54, 7, v51
	v_lshl_add_u64 v[52:53], v[52:53], 0, v[54:55]
	v_lshl_add_u64 v[52:53], v[52:53], 0, v[56:57]
	global_store_dwordx4 v[52:53], v[86:89], off
	s_and_saveexec_b64 s[16:17], s[0:1]
	s_cbranch_execz .LBB0_836
	v_readlane_b32 s56, v252, 1
	v_readlane_b32 s71, v252, 16
	v_readlane_b32 s70, v252, 15
	v_mov_b32_e32 v52, s89
	v_mov_b32_e32 v51, s71
	v_cndmask_b32_e64 v53, v51, v52, s[10:11]
	v_mov_b32_e32 v51, s70
	v_mov_b32_e32 v52, s88
	v_cndmask_b32_e64 v52, v51, v52, s[10:11]
	v_lshlrev_b32_e32 v54, 2, v50
	v_lshl_add_u64 v[50:51], v[52:53], 0, v[54:55]
	v_mul_f32_e32 v52, 0x3b124925, v84
	v_readlane_b32 s57, v252, 2
	v_readlane_b32 s58, v252, 3
	v_readlane_b32 s59, v252, 4
	v_readlane_b32 s60, v252, 5
	v_readlane_b32 s61, v252, 6
	v_readlane_b32 s62, v252, 7
	v_readlane_b32 s63, v252, 8
	v_readlane_b32 s64, v252, 9
	v_readlane_b32 s65, v252, 10
	v_readlane_b32 s66, v252, 11
	v_readlane_b32 s67, v252, 12
	v_readlane_b32 s68, v252, 13
	v_readlane_b32 s69, v252, 14
	global_store_dword v[50:51], v52, off

; DI unsigned xb_ld(unsigned* p) { return __hip_atomic_load(p, __ATOMIC_RELAXED, __HIP_MEMORY_SCOPE_AGENT); }
; DI void phase_scan_prefix(const Params& p, int z, char* smem) {
;   const int tid = threadIdx.x, lane = tid & 63, wave = tid >> 6, g = lane >> 4, l15 = lane & 15;
;   const int bh = z >> 1, sl = (z & 1) * 4 + wave, n0 = sl * 16;
;   if (tid == 0) {
;     unsigned spins = 0u;
;     while (xb_ld(p.bar + 4096 + 128 + bh) < 64u) { __builtin_amdgcn_s_sleep(8); if (++spins > (1u << 22)) break; }
;     __builtin_amdgcn_fence(__ATOMIC_ACQUIRE, "agent");
;     asm volatile("s_waitcnt vmcnt(0)" ::: "memory");
;   }
;   __syncthreads();
.LBB0_843:
	s_andn2_b64 vcc, exec, s[0:1]
	v_cmp_eq_u32_e64 s[0:1], 0, v1
	s_cbranch_vccnz .LBB0_856
	s_ashr_i32 s4, s2, 3
	s_ashr_i32 s5, s4, 31
	s_and_saveexec_b64 s[6:7], s[0:1]
	s_cbranch_execz .LBB0_854
	s_lshl_b64 s[0:1], s[4:5], 2
	s_add_u32 s0, s44, s0
	s_addc_u32 s1, s45, s1
	s_add_u32 s0, s0, 0x4200
	s_addc_u32 s1, s1, 0
	s_mov_b32 s10, 0x400001
	v_mov_b32_e32 v2, 0
	s_branch .LBB0_847

; DI unsigned xb_ld(unsigned* p) { return __hip_atomic_load(p, __ATOMIC_RELAXED, __HIP_MEMORY_SCOPE_AGENT); }
; DI void phase_scan_prefix(const Params& p, int z, char* smem) {
;   const int tid = threadIdx.x, lane = tid & 63, wave = tid >> 6, g = lane >> 4, l15 = lane & 15;
;   const int bh = z >> 1, sl = (z & 1) * 4 + wave, n0 = sl * 16;
;   if (tid == 0) {
;     unsigned spins = 0u;
;     while (xb_ld(p.bar + 4096 + 128 + bh) < 64u) { __builtin_amdgcn_s_sleep(8); if (++spins > (1u << 22)) break; }
;     __builtin_amdgcn_fence(__ATOMIC_ACQUIRE, "agent");
;     asm volatile("s_waitcnt vmcnt(0)" ::: "memory");
;   }
;   __syncthreads();
;   f32x4 S[8];
; #pragma unroll
;   for (int m8 = 0; m8 < 8; m8++) S[m8] = (f32x4){0.f, 0.f, 0.f, 0.f};
;   for (int j = 0; j < 15; j++) {
;     const size_t sbase = (size_t)(bh * 16 + j) * 128 * 128;
;     bf16x8 Sb[4];
; #pragma unroll
;     for (int a = 0; a < 4; a++) Sb[a] = packfrag(S[2 * a], S[2 * a + 1]);
.LBB0_854:
	s_or_b64 exec, exec, s[6:7]
	s_and_b32 s0, s2, 7
	v_mov_b32_e32 v5, s0
	s_lshl_b32 s0, s4, 4
	v_and_b32_e32 v4, 15, v1
	s_ashr_i32 s1, s0, 31
	s_lshl_b64 s[6:7], s[0:1], 15
	v_lshlrev_b32_e32 v2, 8, v4
	s_waitcnt vmcnt(62)
	v_and_b32_e32 v6, 48, v1
	v_readlane_b32 s8, v252, 1
	v_or3_b32 v2, s6, v2, v6
	v_mov_b32_e32 v3, s7
	v_readlane_b32 s14, v252, 7
	v_readlane_b32 s15, v252, 8
	s_lshl_b64 s[4:5], s[4:5], 21
	v_readlane_b32 s9, v252, 2
	s_waitcnt vmcnt(56)
	v_lshl_add_u64 v[36:37], s[14:15], 0, v[2:3]
	v_and_b32_e32 v2, 63, v1
	v_lshlrev_b32_e32 v2, 4, v2
	v_lshlrev_b32_e32 v3, 12, v5
	v_or3_b32 v2, s4, v2, v3
	v_mov_b32_e32 v3, s5
	v_lshl_add_u64 v[2:3], s[8:9], 0, v[2:3]
	s_mov_b64 s[4:5], 0x8800
	s_lshl_b64 s[0:1], s[0:1], 16
	v_lshl_add_u64 v[38:39], v[2:3], 0, s[4:5]
	v_lshl_or_b32 v2, v6, 7, s0
	v_lshlrev_b32_e32 v3, 6, v5
	v_lshlrev_b32_e32 v4, 2, v4
	v_readlane_b32 s10, v252, 3
	v_readlane_b32 s11, v252, 4
	v_readlane_b32 s12, v252, 5
	v_readlane_b32 s13, v252, 6
	v_readlane_b32 s16, v252, 9
	v_readlane_b32 s17, v252, 10
	v_or3_b32 v2, v2, v3, v4
	v_mov_b32_e32 v3, s1
	v_mov_b32_e32 v18, 0
	v_lshl_add_u64 v[40:41], s[16:17], 0, v[2:3]
	s_mov_b64 s[0:1], 0
	s_movk_i32 s3, 0x2000
	s_movk_i32 s6, 0x1000
	s_movk_i32 s7, 0x4000
	s_movk_i32 s8, 0x6000
	s_movk_i32 s9, 0x3000
	s_mov_b32 s10, 0x8000
	s_mov_b32 s11, 0xa000
	s_movk_i32 s12, 0x5000
	s_mov_b32 s13, 0xc000
	s_mov_b32 s14, 0xe000
	s_movk_i32 s15, 0x7000
	s_mov_b64 s[4:5], 0x10000
	v_mov_b32_e32 v19, v18
	v_mov_b32_e32 v20, v18
	v_mov_b32_e32 v21, v18
	v_mov_b32_e32 v24, v18
	v_mov_b32_e32 v25, v18
	v_mov_b32_e32 v26, v18
	v_mov_b32_e32 v27, v18
	v_mov_b32_e32 v28, v18
	v_mov_b32_e32 v29, v18
	v_mov_b32_e32 v30, v18
	v_mov_b32_e32 v31, v18
	v_mov_b32_e32 v32, v18
	v_mov_b32_e32 v33, v18
	v_mov_b32_e32 v34, v18
	v_mov_b32_e32 v35, v18
	v_mov_b32_e32 v2, v18
	v_mov_b32_e32 v3, v18
	v_mov_b32_e32 v4, v18
	v_mov_b32_e32 v5, v18
	v_mov_b32_e32 v6, v18
	v_mov_b32_e32 v7, v18
	v_mov_b32_e32 v8, v18
	v_mov_b32_e32 v9, v18
	v_mov_b32_e32 v10, v18
	v_mov_b32_e32 v11, v18
	v_mov_b32_e32 v12, v18
	v_mov_b32_e32 v13, v18
	v_mov_b32_e32 v14, v18
	v_mov_b32_e32 v15, v18
	v_mov_b32_e32 v16, v18
	v_mov_b32_e32 v17, v18
	s_barrier
	v_readlane_b32 s18, v252, 11
	v_readlane_b32 s19, v252, 12
	v_readlane_b32 s20, v252, 13
	v_readlane_b32 s21, v252, 14
	v_readlane_b32 s22, v252, 15
	v_readlane_b32 s23, v252, 16
	v_readfirstlane_b32 s10, v99
	s_cmp_lg_u32 s10, 0
	s_cbranch_scc1 .LBB0_856
; #define MFMA16(a, b, c) __builtin_amdgcn_mfma_f32_16x16x32_bf16((a), (b), (c), 0, 0, 0)
; DI void phase_scan_prefix(const Params& p, int z, char* smem) {
;     ...
;   f32x4 S[8];
; #pragma unroll
;   for (int m8 = 0; m8 < 8; m8++) S[m8] = (f32x4){0.f, 0.f, 0.f, 0.f};
;   for (int j = 0; j < 15; j++) {
;     const size_t sbase = (size_t)(bh * 16 + j) * 128 * 128;
;     bf16x8 Sb[4];
; #pragma unroll
;     for (int a = 0; a < 4; a++) Sb[a] = packfrag(S[2 * a], S[2 * a + 1]);
; #pragma unroll
;     for (int m8 = 0; m8 < 8; m8++) {
; #pragma unroll
;       for (int r4 = 0; r4 < 4; r4++) S[m8][r4] = p.bseg[sbase + (m8 * 16 + g * 4 + r4) * 128 + n0 + l15];
; #pragma unroll
;       for (int a = 0; a < 4; a++) {
;         const bf16x8 af = *(const bf16x8*)(p.aseg + sbase + (size_t)(m8 * 16 + l15) * 128 + a * 32 + g * 8);
;         S[m8] = MFMA16(af, Sb[a], S[m8]);
;       }
;     }
	s_waitcnt vmcnt(0)
	v_mov_b32_e32 v42, 0
	v_mov_b32_e32 v43, 0
	v_mov_b32_e32 v44, 0
	v_mov_b32_e32 v45, 0
	v_mov_b32_e32 v46, 0
	v_mov_b32_e32 v47, 0
	v_mov_b32_e32 v48, 0
	v_mov_b32_e32 v49, 0
	v_mov_b32_e32 v50, 0
	v_mov_b32_e32 v51, 0
	v_mov_b32_e32 v52, 0
	v_mov_b32_e32 v53, 0
	v_mov_b32_e32 v54, 0
	v_mov_b32_e32 v55, 0
	v_mov_b32_e32 v56, 0
	v_mov_b32_e32 v57, 0
	s_mov_b64 s[0:1], 0x8000
	s_mov_b64 s[4:5], 0x10000
	s_mov_b64 s[6:7], 0x1000
	s_mov_b64 s[8:9], 0x2000
	v_lshl_add_u64 v[218:219], v[36:37], 0, s[6:7]
	v_lshl_add_u64 v[220:221], v[218:219], 0, s[8:9]
	v_lshl_add_u64 v[222:223], v[220:221], 0, s[8:9]
	v_lshl_add_u64 v[224:225], v[222:223], 0, s[8:9]
	v_mov_b32_e32 v226, v40
	v_mov_b32_e32 v227, v41
	v_lshl_add_u64 v[228:229], v[226:227], 0, s[8:9]
	v_lshl_add_u64 v[230:231], v[228:229], 0, s[8:9]
	v_lshl_add_u64 v[232:233], v[230:231], 0, s[8:9]
	v_lshl_add_u64 v[234:235], v[232:233], 0, s[8:9]
	v_lshl_add_u64 v[236:237], v[234:235], 0, s[8:9]
	v_lshl_add_u64 v[238:239], v[236:237], 0, s[8:9]
	v_lshl_add_u64 v[240:241], v[238:239], 0, s[8:9]
	global_load_dword v58, v[226:227], off
	global_load_dword v59, v[226:227], off offset:512
	global_load_dword v60, v[226:227], off offset:1024
	global_load_dword v61, v[226:227], off offset:1536
	v_lshl_add_u64 v[226:227], v[226:227], 0, s[4:5]
	global_load_dwordx4 v[90:93], v[218:219], off offset:-4096
	global_load_dwordx4 v[94:97], v[218:219], off offset:-4032
	global_load_dwordx4 v[98:101], v[218:219], off offset:-3968
	global_load_dwordx4 v[102:105], v[218:219], off offset:-3904
	global_load_dword v62, v[228:229], off
	global_load_dword v63, v[228:229], off offset:512
	global_load_dword v64, v[228:229], off offset:1024
	global_load_dword v65, v[228:229], off offset:1536
	v_lshl_add_u64 v[228:229], v[228:229], 0, s[4:5]
	global_load_dwordx4 v[106:109], v[218:219], off
	global_load_dwordx4 v[110:113], v[218:219], off offset:64
	global_load_dwordx4 v[114:117], v[218:219], off offset:128
	global_load_dwordx4 v[118:121], v[218:219], off offset:192
	v_lshl_add_u64 v[218:219], v[218:219], 0, s[0:1]
	global_load_dword v66, v[230:231], off
	global_load_dword v67, v[230:231], off offset:512
	global_load_dword v68, v[230:231], off offset:1024
	global_load_dword v69, v[230:231], off offset:1536
	v_lshl_add_u64 v[230:231], v[230:231], 0, s[4:5]
	global_load_dwordx4 v[122:125], v[220:221], off offset:-4096
	global_load_dwordx4 v[126:129], v[220:221], off offset:-4032
	global_load_dwordx4 v[130:133], v[220:221], off offset:-3968
	global_load_dwordx4 v[134:137], v[220:221], off offset:-3904
	global_load_dword v70, v[232:233], off
	global_load_dword v71, v[232:233], off offset:512
	global_load_dword v72, v[232:233], off offset:1024
	global_load_dword v73, v[232:233], off offset:1536
	v_lshl_add_u64 v[232:233], v[232:233], 0, s[4:5]
	global_load_dwordx4 v[138:141], v[220:221], off
	global_load_dwordx4 v[142:145], v[220:221], off offset:64
	global_load_dwordx4 v[146:149], v[220:221], off offset:128
	global_load_dwordx4 v[150:153], v[220:221], off offset:192
	v_lshl_add_u64 v[220:221], v[220:221], 0, s[0:1]
	global_load_dword v74, v[234:235], off
	global_load_dword v75, v[234:235], off offset:512
	global_load_dword v76, v[234:235], off offset:1024
	global_load_dword v77, v[234:235], off offset:1536
	v_lshl_add_u64 v[234:235], v[234:235], 0, s[4:5]
	global_load_dwordx4 v[154:157], v[222:223], off offset:-4096
	global_load_dwordx4 v[158:161], v[222:223], off offset:-4032
	global_load_dwordx4 v[162:165], v[222:223], off offset:-3968
	global_load_dwordx4 v[166:169], v[222:223], off offset:-3904
	global_load_dword v78, v[236:237], off
	global_load_dword v79, v[236:237], off offset:512
	global_load_dword v80, v[236:237], off offset:1024
	global_load_dword v81, v[236:237], off offset:1536
	v_lshl_add_u64 v[236:237], v[236:237], 0, s[4:5]
	global_load_dwordx4 v[170:173], v[222:223], off
	global_load_dwordx4 v[174:177], v[222:223], off offset:64
	global_load_dwordx4 v[178:181], v[222:223], off offset:128
	global_load_dwordx4 v[182:185], v[222:223], off offset:192
	v_lshl_add_u64 v[222:223], v[222:223], 0, s[0:1]
	global_load_dword v82, v[238:239], off
	global_load_dword v83, v[238:239], off offset:512
	global_load_dword v84, v[238:239], off offset:1024
	global_load_dword v85, v[238:239], off offset:1536
	v_lshl_add_u64 v[238:239], v[238:239], 0, s[4:5]
	global_load_dwordx4 v[186:189], v[224:225], off offset:-4096
	global_load_dwordx4 v[190:193], v[224:225], off offset:-4032
	global_load_dwordx4 v[194:197], v[224:225], off offset:-3968
	global_load_dwordx4 v[198:201], v[224:225], off offset:-3904
	global_load_dword v86, v[240:241], off
	global_load_dword v87, v[240:241], off offset:512
	global_load_dword v88, v[240:241], off offset:1024
	global_load_dword v89, v[240:241], off offset:1536
	v_lshl_add_u64 v[240:241], v[240:241], 0, s[4:5]
	global_load_dwordx4 v[202:205], v[224:225], off
	global_load_dwordx4 v[206:209], v[224:225], off offset:64
	global_load_dwordx4 v[210:213], v[224:225], off offset:128
	global_load_dwordx4 v[214:217], v[224:225], off offset:192
	v_lshl_add_u64 v[224:225], v[224:225], 0, s[0:1]
	s_mov_b32 s3, 15
